# const_job MOD: silu staging loop unrolled, 12 loads issued up front with counted vmcnt waits
# speedup vs baseline: 1.1767x; 1.0019x over previous
.LBB0_1143:
	s_andn2_b64 vcc, exec, s[0:1]
	s_cbranch_vccnz .LBB0_1060
	s_movk_i32 s0, 0xc00
	v_cmp_gt_i32_e32 vcc, s0, v64
	s_and_saveexec_b64 s[0:1], vcc
	s_cbranch_execz .LBB0_1147
	v_ashrrev_i32_e32 v65, 31, v64
	v_lshlrev_b32_e32 v2, 2, v64
	v_lshl_add_u64 v[0:1], v[64:65], 2, s[38:39]
	v_lshl_add_u64 v[8:9], v[64:65], 2, s[42:43]
	s_mov_b64 s[4:5], 0x1000
	v_lshl_add_u64 v[6:7], v[0:1], 0, s[4:5]
	global_load_dword v10, v[0:1], off
	global_load_dword v11, v[0:1], off offset:1024
	global_load_dword v12, v[0:1], off offset:2048
	global_load_dword v13, v[0:1], off offset:3072
	global_load_dword v14, v[6:7], off
	global_load_dword v15, v[6:7], off offset:1024
	global_load_dword v16, v[6:7], off offset:2048
	global_load_dword v17, v[6:7], off offset:3072
	global_load_dword v18, v[8:9], off
	global_load_dword v19, v[8:9], off offset:1024
	global_load_dword v20, v[8:9], off offset:2048
	global_load_dword v21, v[8:9], off offset:3072
	s_waitcnt vmcnt(11)
	v_mul_f32_e32 v22, 0xbfb8aa3b, v10
	v_exp_f32_e32 v22, v22
	s_nop 0
	v_add_f32_e32 v22, 1.0, v22
	v_rcp_f32_e32 v22, v22
	s_nop 0
	v_mul_f32_e32 v10, v10, v22
	ds_write_b32 v2, v10
	s_waitcnt vmcnt(10)
	v_mul_f32_e32 v22, 0xbfb8aa3b, v11
	v_exp_f32_e32 v22, v22
	s_nop 0
	v_add_f32_e32 v22, 1.0, v22
	v_rcp_f32_e32 v22, v22
	s_nop 0
	v_mul_f32_e32 v11, v11, v22
	ds_write_b32 v2, v11 offset:1024
	s_waitcnt vmcnt(9)
	v_mul_f32_e32 v22, 0xbfb8aa3b, v12
	v_exp_f32_e32 v22, v22
	s_nop 0
	v_add_f32_e32 v22, 1.0, v22
	v_rcp_f32_e32 v22, v22
	s_nop 0
	v_mul_f32_e32 v12, v12, v22
	ds_write_b32 v2, v12 offset:2048
	s_waitcnt vmcnt(8)
	v_mul_f32_e32 v22, 0xbfb8aa3b, v13
	v_exp_f32_e32 v22, v22
	s_nop 0
	v_add_f32_e32 v22, 1.0, v22
	v_rcp_f32_e32 v22, v22
	s_nop 0
	v_mul_f32_e32 v13, v13, v22
	ds_write_b32 v2, v13 offset:3072
	s_waitcnt vmcnt(7)
	v_mul_f32_e32 v22, 0xbfb8aa3b, v14
	v_exp_f32_e32 v22, v22
	s_nop 0
	v_add_f32_e32 v22, 1.0, v22
	v_rcp_f32_e32 v22, v22
	s_nop 0
	v_mul_f32_e32 v14, v14, v22
	ds_write_b32 v2, v14 offset:4096
	s_waitcnt vmcnt(6)
	v_mul_f32_e32 v22, 0xbfb8aa3b, v15
	v_exp_f32_e32 v22, v22
	s_nop 0
	v_add_f32_e32 v22, 1.0, v22
	v_rcp_f32_e32 v22, v22
	s_nop 0
	v_mul_f32_e32 v15, v15, v22
	ds_write_b32 v2, v15 offset:5120
	s_waitcnt vmcnt(5)
	v_mul_f32_e32 v22, 0xbfb8aa3b, v16
	v_exp_f32_e32 v22, v22
	s_nop 0
	v_add_f32_e32 v22, 1.0, v22
	v_rcp_f32_e32 v22, v22
	s_nop 0
	v_mul_f32_e32 v16, v16, v22
	ds_write_b32 v2, v16 offset:6144
	s_waitcnt vmcnt(4)
	v_mul_f32_e32 v22, 0xbfb8aa3b, v17
	v_exp_f32_e32 v22, v22
	s_nop 0
	v_add_f32_e32 v22, 1.0, v22
	v_rcp_f32_e32 v22, v22
	s_nop 0
	v_mul_f32_e32 v17, v17, v22
	ds_write_b32 v2, v17 offset:7168
	s_waitcnt vmcnt(3)
	v_mul_f32_e32 v22, 0xbfb8aa3b, v18
	v_exp_f32_e32 v22, v22
	s_nop 0
	v_add_f32_e32 v22, 1.0, v22
	v_rcp_f32_e32 v22, v22
	s_nop 0
	v_mul_f32_e32 v18, v18, v22
	ds_write_b32 v2, v18 offset:8192
	s_waitcnt vmcnt(2)
	v_mul_f32_e32 v22, 0xbfb8aa3b, v19
	v_exp_f32_e32 v22, v22
	s_nop 0
	v_add_f32_e32 v22, 1.0, v22
	v_rcp_f32_e32 v22, v22
	s_nop 0
	v_mul_f32_e32 v19, v19, v22
	ds_write_b32 v2, v19 offset:9216
	s_waitcnt vmcnt(1)
	v_mul_f32_e32 v22, 0xbfb8aa3b, v20
	v_exp_f32_e32 v22, v22
	s_nop 0
	v_add_f32_e32 v22, 1.0, v22
	v_rcp_f32_e32 v22, v22
	s_nop 0
	v_mul_f32_e32 v20, v20, v22
	ds_write_b32 v2, v20 offset:10240
	s_waitcnt vmcnt(0)
	v_mul_f32_e32 v22, 0xbfb8aa3b, v21
	v_exp_f32_e32 v22, v22
	s_nop 0
	v_add_f32_e32 v22, 1.0, v22
	v_rcp_f32_e32 v22, v22
	s_nop 0
	v_mul_f32_e32 v21, v21, v22
	ds_write_b32 v2, v21 offset:11264
